# v107 + ph_out: hand-written residual epilogue (as in ph_down: x loads pipelined 4 rows deep, dwordx4 bf16 stores via v_permlane16_swap)
# speedup vs baseline: 1.0099x; 1.0014x over previous
; DI unsigned pk2(float lo, float hi) { unsigned r; asm("v_cvt_pk_bf16_f32 %0, %1, %2" : "=v"(r) : "v"(lo), "v"(hi)); return r; }
;     DI void operator()(const f32x4 (&acc)[2][2][4][2], const Unit& u, int wr, int wc, int fr, int fq) const {
;         const int col0 = u.pn * BM + wc * 32 + 4 * fq;
; #pragma unroll
;         for (int ai = 0; ai < 2; ++ai) {
;             const int rowa = u.pm * BM + ai * HALF + wr * 64 + fr;
;             f32x4 xo[4][2][2];
; #pragma unroll
;             for (int m = 0; m < 4; ++m)
; #pragma unroll
;                 for (int bj = 0; bj < 2; ++bj)
; #pragma unroll
;                     for (int n = 0; n < 2; ++n) xo[m][bj][n] = *(const f32x4*)(x + (size_t)(rowa + m * 16) * D + col0 + bj * HALF + n * 16);
;             asm volatile("" ::: "memory");
; #pragma unroll
;             for (int m = 0; m < 4; ++m) {
;                 const int row = rowa + m * 16;
;                 float* xr = x + (size_t)row * D + col0; bf16_t* br = xb + (size_t)row * D + col0;
;                 float ss = 0.f;
; #pragma unroll
;                 for (int bj = 0; bj < 2; ++bj)
; #pragma unroll
;                     for (int n = 0; n < 2; ++n) {
;                         const f32x4 xn = xo[m][bj][n] + acc[ai][bj][m][n] * s;
;                         *(f32x4*)(xr + bj * HALF + n * 16) = xn;
;                         u32x2 w; w.x = pk2(xn[0], xn[1]); w.y = pk2(xn[2], xn[3]);
;                         *(u32x2*)(br + bj * HALF + n * 16) = w;
;                         ss += (xn[0] * xn[0] + xn[1] * xn[1]) + (xn[2] * xn[2] + xn[3] * xn[3]);
;                     }
;                 ss += __shfl_xor(ss, 16); ss += __shfl_xor(ss, 32);
;                 if (fq == 0) slots[(size_t)row * 16 + u.pn * 4 + wc] = ss;
;             }
.LBB0_620:
	v_lshl_add_u32 v218, s64, 8, v1
	v_lshl_or_b32 v219, s62, 8, v216
	v_lshlrev_b32_e32 v220, 12, v218
	v_lshl_add_u32 v220, v219, 2, v220
	global_load_dwordx4 v[114:117], v220, s[48:49]
	global_load_dwordx4 v[118:121], v220, s[48:49] offset:64
	global_load_dwordx4 v[122:125], v220, s[48:49] offset:512
	global_load_dwordx4 v[126:129], v220, s[48:49] offset:576
	v_add_u32_e32 v149, 0x10000, v220
	global_load_dwordx4 v[162:165], v149, s[48:49]
	global_load_dwordx4 v[166:169], v149, s[48:49] offset:64
	global_load_dwordx4 v[170:173], v149, s[48:49] offset:512
	global_load_dwordx4 v[174:177], v149, s[48:49] offset:576
	v_add_u32_e32 v149, 0x20000, v220
	global_load_dwordx4 v[200:203], v149, s[48:49]
	global_load_dwordx4 v[204:207], v149, s[48:49] offset:64
	global_load_dwordx4 v[208:211], v149, s[48:49] offset:512
	global_load_dwordx4 v[212:215], v149, s[48:49] offset:576
	v_add_u32_e32 v149, 0x30000, v220
	global_load_dwordx4 v[134:137], v149, s[48:49]
	global_load_dwordx4 v[138:141], v149, s[48:49] offset:64
	global_load_dwordx4 v[186:189], v149, s[48:49] offset:512
	global_load_dwordx4 v[190:193], v149, s[48:49] offset:576
	v_lshlrev_b32_e32 v221, 11, v218
	v_and_b32_e32 v222, 16, v249
	v_lshl_add_u32 v221, v219, 1, v221
	v_lshrrev_b32_e32 v222, 1, v222
	s_lshl_b32 s98, s62, 4
	s_lshl_b32 s99, s45, 2
	v_lshl_add_u32 v222, v222, 1, v222
	s_add_i32 s98, s98, s99
	v_lshlrev_b32_e32 v223, 6, v218
	v_add_u32_e32 v221, v221, v222
	v_add_u32_e32 v223, s98, v223
	s_waitcnt vmcnt(12)
	v_pk_fma_f32 v[158:159], v[158:159], 1.0, v[114:115] op_sel_hi:[1,0,1]
	v_pk_fma_f32 v[160:161], v[160:161], 1.0, v[116:117] op_sel_hi:[1,0,1]
	v_pk_fma_f32 v[150:151], v[150:151], 1.0, v[118:119] op_sel_hi:[1,0,1]
	v_pk_fma_f32 v[152:153], v[152:153], 1.0, v[120:121] op_sel_hi:[1,0,1]
	v_pk_fma_f32 v[142:143], v[142:143], 1.0, v[122:123] op_sel_hi:[1,0,1]
	v_pk_fma_f32 v[144:145], v[144:145], 1.0, v[124:125] op_sel_hi:[1,0,1]
	v_pk_fma_f32 v[130:131], v[130:131], 1.0, v[126:127] op_sel_hi:[1,0,1]
	v_pk_fma_f32 v[132:133], v[132:133], 1.0, v[128:129] op_sel_hi:[1,0,1]
	v_add_u32_e32 v149, 0x80000, v220
	global_load_dwordx4 v[114:117], v149, s[48:49]
	global_load_dwordx4 v[118:121], v149, s[48:49] offset:64
	global_load_dwordx4 v[122:125], v149, s[48:49] offset:512
	global_load_dwordx4 v[126:129], v149, s[48:49] offset:576
	global_store_dwordx4 v220, v[158:161], s[48:49]
	global_store_dwordx4 v220, v[150:153], s[48:49] offset:64
	global_store_dwordx4 v220, v[142:145], s[48:49] offset:512
	global_store_dwordx4 v220, v[130:133], s[48:49] offset:576
	v_cvt_pk_bf16_f32 v224, v158, v159
	v_cvt_pk_bf16_f32 v225, v160, v161
	v_cvt_pk_bf16_f32 v226, v150, v151
	v_cvt_pk_bf16_f32 v227, v152, v153
	v_mul_f32_e32 v154, v159, v159
	v_mul_f32_e32 v155, v161, v161
	v_fmac_f32_e32 v154, v158, v158
	v_fmac_f32_e32 v155, v160, v160
	v_add_f32_e32 v156, v154, v155
	v_mul_f32_e32 v154, v151, v151
	v_mul_f32_e32 v155, v153, v153
	v_fmac_f32_e32 v154, v150, v150
	v_fmac_f32_e32 v155, v152, v152
	v_add_f32_e32 v154, v154, v155
	v_add_f32_e32 v156, v156, v154
	v_permlane16_swap_b32_e32 v224, v226
	v_permlane16_swap_b32_e32 v225, v227
	global_store_dwordx4 v221, v[224:227], s[50:51]
	v_cvt_pk_bf16_f32 v228, v142, v143
	v_cvt_pk_bf16_f32 v229, v144, v145
	v_cvt_pk_bf16_f32 v230, v130, v131
	v_cvt_pk_bf16_f32 v231, v132, v133
	v_mul_f32_e32 v154, v143, v143
	v_mul_f32_e32 v155, v145, v145
	v_fmac_f32_e32 v154, v142, v142
	v_fmac_f32_e32 v155, v144, v144
	v_add_f32_e32 v154, v154, v155
	v_add_f32_e32 v156, v156, v154
	v_mul_f32_e32 v154, v131, v131
	v_mul_f32_e32 v155, v133, v133
	v_fmac_f32_e32 v154, v130, v130
	v_fmac_f32_e32 v155, v132, v132
	v_add_f32_e32 v154, v154, v155
	v_add_f32_e32 v156, v156, v154
	v_permlane16_swap_b32_e32 v228, v230
	v_permlane16_swap_b32_e32 v229, v231
	global_store_dwordx4 v221, v[228:231], s[50:51] offset:256
	v_mov_b32_e32 v157, v156
	s_nop 1
	v_permlane16_swap_b32_e32 v157, v156
	v_add_f32_e32 v156, v157, v156
	v_mov_b32_e32 v157, v156
	s_nop 1
	v_permlane32_swap_b32_e32 v157, v156
	v_add_f32_e32 v156, v157, v156
	global_store_dword v223, v156, s[46:47]
	s_waitcnt vmcnt(19)
	v_pk_fma_f32 v[110:111], v[110:111], 1.0, v[162:163] op_sel_hi:[1,0,1]
	v_pk_fma_f32 v[112:113], v[112:113], 1.0, v[164:165] op_sel_hi:[1,0,1]
	v_pk_fma_f32 v[106:107], v[106:107], 1.0, v[166:167] op_sel_hi:[1,0,1]
	v_pk_fma_f32 v[108:109], v[108:109], 1.0, v[168:169] op_sel_hi:[1,0,1]
	v_pk_fma_f32 v[102:103], v[102:103], 1.0, v[170:171] op_sel_hi:[1,0,1]
	v_pk_fma_f32 v[104:105], v[104:105], 1.0, v[172:173] op_sel_hi:[1,0,1]
	v_pk_fma_f32 v[98:99], v[98:99], 1.0, v[174:175] op_sel_hi:[1,0,1]
	v_pk_fma_f32 v[100:101], v[100:101], 1.0, v[176:177] op_sel_hi:[1,0,1]
	v_add_u32_e32 v149, 0x90000, v220
	global_load_dwordx4 v[162:165], v149, s[48:49]
	global_load_dwordx4 v[166:169], v149, s[48:49] offset:64
	global_load_dwordx4 v[170:173], v149, s[48:49] offset:512
	global_load_dwordx4 v[174:177], v149, s[48:49] offset:576
	v_add_u32_e32 v146, 0x10000, v220
	v_add_u32_e32 v147, 0x8000, v221
	v_add_u32_e32 v148, 0x400, v223
	global_store_dwordx4 v146, v[110:113], s[48:49]
	global_store_dwordx4 v146, v[106:109], s[48:49] offset:64
	global_store_dwordx4 v146, v[102:105], s[48:49] offset:512
	global_store_dwordx4 v146, v[98:101], s[48:49] offset:576
	v_cvt_pk_bf16_f32 v224, v110, v111
	v_cvt_pk_bf16_f32 v225, v112, v113
	v_cvt_pk_bf16_f32 v226, v106, v107
	v_cvt_pk_bf16_f32 v227, v108, v109
	v_mul_f32_e32 v154, v111, v111
	v_mul_f32_e32 v155, v113, v113
	v_fmac_f32_e32 v154, v110, v110
	v_fmac_f32_e32 v155, v112, v112
	v_add_f32_e32 v156, v154, v155
	v_mul_f32_e32 v154, v107, v107
	v_mul_f32_e32 v155, v109, v109
	v_fmac_f32_e32 v154, v106, v106
	v_fmac_f32_e32 v155, v108, v108
	v_add_f32_e32 v154, v154, v155
	v_add_f32_e32 v156, v156, v154
	v_permlane16_swap_b32_e32 v224, v226
	v_permlane16_swap_b32_e32 v225, v227
	global_store_dwordx4 v147, v[224:227], s[50:51]
	v_cvt_pk_bf16_f32 v228, v102, v103
	v_cvt_pk_bf16_f32 v229, v104, v105
	v_cvt_pk_bf16_f32 v230, v98, v99
	v_cvt_pk_bf16_f32 v231, v100, v101
	v_mul_f32_e32 v154, v103, v103
	v_mul_f32_e32 v155, v105, v105
	v_fmac_f32_e32 v154, v102, v102
	v_fmac_f32_e32 v155, v104, v104
	v_add_f32_e32 v154, v154, v155
	v_add_f32_e32 v156, v156, v154
	v_mul_f32_e32 v154, v99, v99
	v_mul_f32_e32 v155, v101, v101
	v_fmac_f32_e32 v154, v98, v98
	v_fmac_f32_e32 v155, v100, v100
	v_add_f32_e32 v154, v154, v155
	v_add_f32_e32 v156, v156, v154
	v_permlane16_swap_b32_e32 v228, v230
	v_permlane16_swap_b32_e32 v229, v231
	global_store_dwordx4 v147, v[228:231], s[50:51] offset:256
	v_mov_b32_e32 v157, v156
	s_nop 1
	v_permlane16_swap_b32_e32 v157, v156
	v_add_f32_e32 v156, v157, v156
	v_mov_b32_e32 v157, v156
	s_nop 1
	v_permlane32_swap_b32_e32 v157, v156
	v_add_f32_e32 v156, v157, v156
	global_store_dword v148, v156, s[46:47]
	s_waitcnt vmcnt(26)
; DI unsigned pk2(float lo, float hi) { unsigned r; asm("v_cvt_pk_bf16_f32 %0, %1, %2" : "=v"(r) : "v"(lo), "v"(hi)); return r; }
;     DI void operator()(const f32x4 (&acc)[2][2][4][2], const Unit& u, int wr, int wc, int fr, int fq) const {
;     ...
;                     for (int n = 0; n < 2; ++n) xo[m][bj][n] = *(const f32x4*)(x + (size_t)(rowa + m * 16) * D + col0 + bj * HALF + n * 16);
;             asm volatile("" ::: "memory");
; #pragma unroll
;             for (int m = 0; m < 4; ++m) {
;                 const int row = rowa + m * 16;
;                 float* xr = x + (size_t)row * D + col0; bf16_t* br = xb + (size_t)row * D + col0;
;                 float ss = 0.f;
; #pragma unroll
;                 for (int bj = 0; bj < 2; ++bj)
; #pragma unroll
;                     for (int n = 0; n < 2; ++n) {
;                         const f32x4 xn = xo[m][bj][n] + acc[ai][bj][m][n] * s;
;                         *(f32x4*)(xr + bj * HALF + n * 16) = xn;
;                         u32x2 w; w.x = pk2(xn[0], xn[1]); w.y = pk2(xn[2], xn[3]);
;                         *(u32x2*)(br + bj * HALF + n * 16) = w;
;                         ss += (xn[0] * xn[0] + xn[1] * xn[1]) + (xn[2] * xn[2] + xn[3] * xn[3]);
;                     }
;                 ss += __shfl_xor(ss, 16); ss += __shfl_xor(ss, 32);
;                 if (fq == 0) slots[(size_t)row * 16 + u.pn * 4 + wc] = ss;
;             }
	v_pk_fma_f32 v[94:95], v[94:95], 1.0, v[200:201] op_sel_hi:[1,0,1]
	v_pk_fma_f32 v[96:97], v[96:97], 1.0, v[202:203] op_sel_hi:[1,0,1]
	v_pk_fma_f32 v[90:91], v[90:91], 1.0, v[204:205] op_sel_hi:[1,0,1]
	v_pk_fma_f32 v[92:93], v[92:93], 1.0, v[206:207] op_sel_hi:[1,0,1]
	v_pk_fma_f32 v[86:87], v[86:87], 1.0, v[208:209] op_sel_hi:[1,0,1]
	v_pk_fma_f32 v[88:89], v[88:89], 1.0, v[210:211] op_sel_hi:[1,0,1]
	v_pk_fma_f32 v[82:83], v[82:83], 1.0, v[212:213] op_sel_hi:[1,0,1]
	v_pk_fma_f32 v[84:85], v[84:85], 1.0, v[214:215] op_sel_hi:[1,0,1]
	v_add_u32_e32 v149, 0xa0000, v220
	global_load_dwordx4 v[200:203], v149, s[48:49]
	global_load_dwordx4 v[204:207], v149, s[48:49] offset:64
	global_load_dwordx4 v[208:211], v149, s[48:49] offset:512
	global_load_dwordx4 v[212:215], v149, s[48:49] offset:576
	v_add_u32_e32 v146, 0x20000, v220
	v_add_u32_e32 v147, 0x10000, v221
	v_add_u32_e32 v148, 0x800, v223
	global_store_dwordx4 v146, v[94:97], s[48:49]
	global_store_dwordx4 v146, v[90:93], s[48:49] offset:64
	global_store_dwordx4 v146, v[86:89], s[48:49] offset:512
	global_store_dwordx4 v146, v[82:85], s[48:49] offset:576
	v_cvt_pk_bf16_f32 v224, v94, v95
	v_cvt_pk_bf16_f32 v225, v96, v97
	v_cvt_pk_bf16_f32 v226, v90, v91
	v_cvt_pk_bf16_f32 v227, v92, v93
	v_mul_f32_e32 v154, v95, v95
	v_mul_f32_e32 v155, v97, v97
	v_fmac_f32_e32 v154, v94, v94
	v_fmac_f32_e32 v155, v96, v96
	v_add_f32_e32 v156, v154, v155
	v_mul_f32_e32 v154, v91, v91
	v_mul_f32_e32 v155, v93, v93
	v_fmac_f32_e32 v154, v90, v90
	v_fmac_f32_e32 v155, v92, v92
	v_add_f32_e32 v154, v154, v155
	v_add_f32_e32 v156, v156, v154
	v_permlane16_swap_b32_e32 v224, v226
	v_permlane16_swap_b32_e32 v225, v227
	global_store_dwordx4 v147, v[224:227], s[50:51]
	v_cvt_pk_bf16_f32 v228, v86, v87
	v_cvt_pk_bf16_f32 v229, v88, v89
	v_cvt_pk_bf16_f32 v230, v82, v83
	v_cvt_pk_bf16_f32 v231, v84, v85
	v_mul_f32_e32 v154, v87, v87
	v_mul_f32_e32 v155, v89, v89
	v_fmac_f32_e32 v154, v86, v86
	v_fmac_f32_e32 v155, v88, v88
	v_add_f32_e32 v154, v154, v155
	v_add_f32_e32 v156, v156, v154
	v_mul_f32_e32 v154, v83, v83
	v_mul_f32_e32 v155, v85, v85
	v_fmac_f32_e32 v154, v82, v82
	v_fmac_f32_e32 v155, v84, v84
	v_add_f32_e32 v154, v154, v155
	v_add_f32_e32 v156, v156, v154
	v_permlane16_swap_b32_e32 v228, v230
	v_permlane16_swap_b32_e32 v229, v231
	global_store_dwordx4 v147, v[228:231], s[50:51] offset:256
	v_mov_b32_e32 v157, v156
	s_nop 1
	v_permlane16_swap_b32_e32 v157, v156
	v_add_f32_e32 v156, v157, v156
	v_mov_b32_e32 v157, v156
	s_nop 1
	v_permlane32_swap_b32_e32 v157, v156
	v_add_f32_e32 v156, v157, v156
	global_store_dword v148, v156, s[46:47]
	s_waitcnt vmcnt(33)
	v_pk_fma_f32 v[78:79], v[78:79], 1.0, v[134:135] op_sel_hi:[1,0,1]
	v_pk_fma_f32 v[80:81], v[80:81], 1.0, v[136:137] op_sel_hi:[1,0,1]
	v_pk_fma_f32 v[74:75], v[74:75], 1.0, v[138:139] op_sel_hi:[1,0,1]
	v_pk_fma_f32 v[76:77], v[76:77], 1.0, v[140:141] op_sel_hi:[1,0,1]
	v_pk_fma_f32 v[70:71], v[70:71], 1.0, v[186:187] op_sel_hi:[1,0,1]
	v_pk_fma_f32 v[72:73], v[72:73], 1.0, v[188:189] op_sel_hi:[1,0,1]
	v_pk_fma_f32 v[66:67], v[66:67], 1.0, v[190:191] op_sel_hi:[1,0,1]
	v_pk_fma_f32 v[68:69], v[68:69], 1.0, v[192:193] op_sel_hi:[1,0,1]
	v_add_u32_e32 v149, 0xb0000, v220
	global_load_dwordx4 v[134:137], v149, s[48:49]
	global_load_dwordx4 v[138:141], v149, s[48:49] offset:64
	global_load_dwordx4 v[186:189], v149, s[48:49] offset:512
	global_load_dwordx4 v[190:193], v149, s[48:49] offset:576
	v_add_u32_e32 v146, 0x30000, v220
	v_add_u32_e32 v147, 0x18000, v221
	v_add_u32_e32 v148, 0xc00, v223
	global_store_dwordx4 v146, v[78:81], s[48:49]
	global_store_dwordx4 v146, v[74:77], s[48:49] offset:64
	global_store_dwordx4 v146, v[70:73], s[48:49] offset:512
	global_store_dwordx4 v146, v[66:69], s[48:49] offset:576
	v_cvt_pk_bf16_f32 v224, v78, v79
	v_cvt_pk_bf16_f32 v225, v80, v81
	v_cvt_pk_bf16_f32 v226, v74, v75
	v_cvt_pk_bf16_f32 v227, v76, v77
	v_mul_f32_e32 v154, v79, v79
	v_mul_f32_e32 v155, v81, v81
	v_fmac_f32_e32 v154, v78, v78
	v_fmac_f32_e32 v155, v80, v80
	v_add_f32_e32 v156, v154, v155
	v_mul_f32_e32 v154, v75, v75
	v_mul_f32_e32 v155, v77, v77
	v_fmac_f32_e32 v154, v74, v74
	v_fmac_f32_e32 v155, v76, v76
	v_add_f32_e32 v154, v154, v155
	v_add_f32_e32 v156, v156, v154
	v_permlane16_swap_b32_e32 v224, v226
	v_permlane16_swap_b32_e32 v225, v227
	global_store_dwordx4 v147, v[224:227], s[50:51]
	v_cvt_pk_bf16_f32 v228, v70, v71
	v_cvt_pk_bf16_f32 v229, v72, v73
	v_cvt_pk_bf16_f32 v230, v66, v67
	v_cvt_pk_bf16_f32 v231, v68, v69
	v_mul_f32_e32 v154, v71, v71
	v_mul_f32_e32 v155, v73, v73
	v_fmac_f32_e32 v154, v70, v70
	v_fmac_f32_e32 v155, v72, v72
	v_add_f32_e32 v154, v154, v155
	v_add_f32_e32 v156, v156, v154
	v_mul_f32_e32 v154, v67, v67
	v_mul_f32_e32 v155, v69, v69
	v_fmac_f32_e32 v154, v66, v66
	v_fmac_f32_e32 v155, v68, v68
	v_add_f32_e32 v154, v154, v155
	v_add_f32_e32 v156, v156, v154
	v_permlane16_swap_b32_e32 v228, v230
	v_permlane16_swap_b32_e32 v229, v231
	global_store_dwordx4 v147, v[228:231], s[50:51] offset:256
	v_mov_b32_e32 v157, v156
	s_nop 1
	v_permlane16_swap_b32_e32 v157, v156
	v_add_f32_e32 v156, v157, v156
	v_mov_b32_e32 v157, v156
	s_nop 1
	v_permlane32_swap_b32_e32 v157, v156
	v_add_f32_e32 v156, v157, v156
	global_store_dword v148, v156, s[46:47]
	s_waitcnt vmcnt(40)
; DI unsigned pk2(float lo, float hi) { unsigned r; asm("v_cvt_pk_bf16_f32 %0, %1, %2" : "=v"(r) : "v"(lo), "v"(hi)); return r; }
;     DI void operator()(const f32x4 (&acc)[2][2][4][2], const Unit& u, int wr, int wc, int fr, int fq) const {
;     ...
;                     for (int n = 0; n < 2; ++n) xo[m][bj][n] = *(const f32x4*)(x + (size_t)(rowa + m * 16) * D + col0 + bj * HALF + n * 16);
;             asm volatile("" ::: "memory");
; #pragma unroll
;             for (int m = 0; m < 4; ++m) {
;                 const int row = rowa + m * 16;
;                 float* xr = x + (size_t)row * D + col0; bf16_t* br = xb + (size_t)row * D + col0;
;                 float ss = 0.f;
; #pragma unroll
;                 for (int bj = 0; bj < 2; ++bj)
; #pragma unroll
;                     for (int n = 0; n < 2; ++n) {
;                         const f32x4 xn = xo[m][bj][n] + acc[ai][bj][m][n] * s;
;                         *(f32x4*)(xr + bj * HALF + n * 16) = xn;
;                         u32x2 w; w.x = pk2(xn[0], xn[1]); w.y = pk2(xn[2], xn[3]);
;                         *(u32x2*)(br + bj * HALF + n * 16) = w;
;                         ss += (xn[0] * xn[0] + xn[1] * xn[1]) + (xn[2] * xn[2] + xn[3] * xn[3]);
;                     }
;                 ss += __shfl_xor(ss, 16); ss += __shfl_xor(ss, 32);
;                 if (fq == 0) slots[(size_t)row * 16 + u.pn * 4 + wc] = ss;
;             }
	v_pk_fma_f32 v[62:63], v[62:63], 1.0, v[114:115] op_sel_hi:[1,0,1]
	v_pk_fma_f32 v[64:65], v[64:65], 1.0, v[116:117] op_sel_hi:[1,0,1]
	v_pk_fma_f32 v[58:59], v[58:59], 1.0, v[118:119] op_sel_hi:[1,0,1]
	v_pk_fma_f32 v[60:61], v[60:61], 1.0, v[120:121] op_sel_hi:[1,0,1]
	v_pk_fma_f32 v[54:55], v[54:55], 1.0, v[122:123] op_sel_hi:[1,0,1]
	v_pk_fma_f32 v[56:57], v[56:57], 1.0, v[124:125] op_sel_hi:[1,0,1]
	v_pk_fma_f32 v[50:51], v[50:51], 1.0, v[126:127] op_sel_hi:[1,0,1]
	v_pk_fma_f32 v[52:53], v[52:53], 1.0, v[128:129] op_sel_hi:[1,0,1]
	v_add_u32_e32 v146, 0x80000, v220
	v_add_u32_e32 v147, 0x40000, v221
	v_add_u32_e32 v148, 0x2000, v223
	global_store_dwordx4 v146, v[62:65], s[48:49]
	global_store_dwordx4 v146, v[58:61], s[48:49] offset:64
	global_store_dwordx4 v146, v[54:57], s[48:49] offset:512
	global_store_dwordx4 v146, v[50:53], s[48:49] offset:576
	v_cvt_pk_bf16_f32 v224, v62, v63
	v_cvt_pk_bf16_f32 v225, v64, v65
	v_cvt_pk_bf16_f32 v226, v58, v59
	v_cvt_pk_bf16_f32 v227, v60, v61
	v_mul_f32_e32 v154, v63, v63
	v_mul_f32_e32 v155, v65, v65
	v_fmac_f32_e32 v154, v62, v62
	v_fmac_f32_e32 v155, v64, v64
	v_add_f32_e32 v156, v154, v155
	v_mul_f32_e32 v154, v59, v59
	v_mul_f32_e32 v155, v61, v61
	v_fmac_f32_e32 v154, v58, v58
	v_fmac_f32_e32 v155, v60, v60
	v_add_f32_e32 v154, v154, v155
	v_add_f32_e32 v156, v156, v154
	v_permlane16_swap_b32_e32 v224, v226
	v_permlane16_swap_b32_e32 v225, v227
	global_store_dwordx4 v147, v[224:227], s[50:51]
	v_cvt_pk_bf16_f32 v228, v54, v55
	v_cvt_pk_bf16_f32 v229, v56, v57
	v_cvt_pk_bf16_f32 v230, v50, v51
	v_cvt_pk_bf16_f32 v231, v52, v53
	v_mul_f32_e32 v154, v55, v55
	v_mul_f32_e32 v155, v57, v57
	v_fmac_f32_e32 v154, v54, v54
	v_fmac_f32_e32 v155, v56, v56
	v_add_f32_e32 v154, v154, v155
	v_add_f32_e32 v156, v156, v154
	v_mul_f32_e32 v154, v51, v51
	v_mul_f32_e32 v155, v53, v53
	v_fmac_f32_e32 v154, v50, v50
	v_fmac_f32_e32 v155, v52, v52
	v_add_f32_e32 v154, v154, v155
	v_add_f32_e32 v156, v156, v154
	v_permlane16_swap_b32_e32 v228, v230
	v_permlane16_swap_b32_e32 v229, v231
	global_store_dwordx4 v147, v[228:231], s[50:51] offset:256
	v_mov_b32_e32 v157, v156
	s_nop 1
	v_permlane16_swap_b32_e32 v157, v156
	v_add_f32_e32 v156, v157, v156
	v_mov_b32_e32 v157, v156
	s_nop 1
	v_permlane32_swap_b32_e32 v157, v156
	v_add_f32_e32 v156, v157, v156
	global_store_dword v148, v156, s[46:47]
	s_waitcnt vmcnt(36)
	v_pk_fma_f32 v[46:47], v[46:47], 1.0, v[162:163] op_sel_hi:[1,0,1]
	v_pk_fma_f32 v[48:49], v[48:49], 1.0, v[164:165] op_sel_hi:[1,0,1]
	v_pk_fma_f32 v[42:43], v[42:43], 1.0, v[166:167] op_sel_hi:[1,0,1]
	v_pk_fma_f32 v[44:45], v[44:45], 1.0, v[168:169] op_sel_hi:[1,0,1]
	v_pk_fma_f32 v[38:39], v[38:39], 1.0, v[170:171] op_sel_hi:[1,0,1]
	v_pk_fma_f32 v[40:41], v[40:41], 1.0, v[172:173] op_sel_hi:[1,0,1]
	v_pk_fma_f32 v[34:35], v[34:35], 1.0, v[174:175] op_sel_hi:[1,0,1]
	v_pk_fma_f32 v[36:37], v[36:37], 1.0, v[176:177] op_sel_hi:[1,0,1]
	v_add_u32_e32 v146, 0x90000, v220
	v_add_u32_e32 v147, 0x48000, v221
	v_add_u32_e32 v148, 0x2400, v223
	global_store_dwordx4 v146, v[46:49], s[48:49]
	global_store_dwordx4 v146, v[42:45], s[48:49] offset:64
	global_store_dwordx4 v146, v[38:41], s[48:49] offset:512
	global_store_dwordx4 v146, v[34:37], s[48:49] offset:576
	v_cvt_pk_bf16_f32 v224, v46, v47
	v_cvt_pk_bf16_f32 v225, v48, v49
	v_cvt_pk_bf16_f32 v226, v42, v43
	v_cvt_pk_bf16_f32 v227, v44, v45
	v_mul_f32_e32 v154, v47, v47
	v_mul_f32_e32 v155, v49, v49
	v_fmac_f32_e32 v154, v46, v46
	v_fmac_f32_e32 v155, v48, v48
	v_add_f32_e32 v156, v154, v155
	v_mul_f32_e32 v154, v43, v43
	v_mul_f32_e32 v155, v45, v45
	v_fmac_f32_e32 v154, v42, v42
	v_fmac_f32_e32 v155, v44, v44
	v_add_f32_e32 v154, v154, v155
	v_add_f32_e32 v156, v156, v154
	v_permlane16_swap_b32_e32 v224, v226
	v_permlane16_swap_b32_e32 v225, v227
	global_store_dwordx4 v147, v[224:227], s[50:51]
	v_cvt_pk_bf16_f32 v228, v38, v39
	v_cvt_pk_bf16_f32 v229, v40, v41
	v_cvt_pk_bf16_f32 v230, v34, v35
	v_cvt_pk_bf16_f32 v231, v36, v37
	v_mul_f32_e32 v154, v39, v39
	v_mul_f32_e32 v155, v41, v41
	v_fmac_f32_e32 v154, v38, v38
	v_fmac_f32_e32 v155, v40, v40
	v_add_f32_e32 v154, v154, v155
	v_add_f32_e32 v156, v156, v154
	v_mul_f32_e32 v154, v35, v35
	v_mul_f32_e32 v155, v37, v37
	v_fmac_f32_e32 v154, v34, v34
	v_fmac_f32_e32 v155, v36, v36
	v_add_f32_e32 v154, v154, v155
	v_add_f32_e32 v156, v156, v154
	v_permlane16_swap_b32_e32 v228, v230
	v_permlane16_swap_b32_e32 v229, v231
	global_store_dwordx4 v147, v[228:231], s[50:51] offset:256
	v_mov_b32_e32 v157, v156
	s_nop 1
	v_permlane16_swap_b32_e32 v157, v156
	v_add_f32_e32 v156, v157, v156
	v_mov_b32_e32 v157, v156
	s_nop 1
	v_permlane32_swap_b32_e32 v157, v156
	v_add_f32_e32 v156, v157, v156
	global_store_dword v148, v156, s[46:47]
	s_waitcnt vmcnt(32)
; DI unsigned pk2(float lo, float hi) { unsigned r; asm("v_cvt_pk_bf16_f32 %0, %1, %2" : "=v"(r) : "v"(lo), "v"(hi)); return r; }
;     DI void operator()(const f32x4 (&acc)[2][2][4][2], const Unit& u, int wr, int wc, int fr, int fq) const {
;     ...
;                     for (int n = 0; n < 2; ++n) xo[m][bj][n] = *(const f32x4*)(x + (size_t)(rowa + m * 16) * D + col0 + bj * HALF + n * 16);
;             asm volatile("" ::: "memory");
; #pragma unroll
;             for (int m = 0; m < 4; ++m) {
;                 const int row = rowa + m * 16;
;                 float* xr = x + (size_t)row * D + col0; bf16_t* br = xb + (size_t)row * D + col0;
;                 float ss = 0.f;
; #pragma unroll
;                 for (int bj = 0; bj < 2; ++bj)
; #pragma unroll
;                     for (int n = 0; n < 2; ++n) {
;                         const f32x4 xn = xo[m][bj][n] + acc[ai][bj][m][n] * s;
;                         *(f32x4*)(xr + bj * HALF + n * 16) = xn;
;                         u32x2 w; w.x = pk2(xn[0], xn[1]); w.y = pk2(xn[2], xn[3]);
;                         *(u32x2*)(br + bj * HALF + n * 16) = w;
;                         ss += (xn[0] * xn[0] + xn[1] * xn[1]) + (xn[2] * xn[2] + xn[3] * xn[3]);
;                     }
;                 ss += __shfl_xor(ss, 16); ss += __shfl_xor(ss, 32);
;                 if (fq == 0) slots[(size_t)row * 16 + u.pn * 4 + wc] = ss;
;             }
;             asm volatile("" ::: "memory");
;         }
;     }
	v_pk_fma_f32 v[30:31], v[30:31], 1.0, v[200:201] op_sel_hi:[1,0,1]
	v_pk_fma_f32 v[32:33], v[32:33], 1.0, v[202:203] op_sel_hi:[1,0,1]
	v_pk_fma_f32 v[26:27], v[26:27], 1.0, v[204:205] op_sel_hi:[1,0,1]
	v_pk_fma_f32 v[28:29], v[28:29], 1.0, v[206:207] op_sel_hi:[1,0,1]
	v_pk_fma_f32 v[22:23], v[22:23], 1.0, v[208:209] op_sel_hi:[1,0,1]
	v_pk_fma_f32 v[24:25], v[24:25], 1.0, v[210:211] op_sel_hi:[1,0,1]
	v_pk_fma_f32 v[18:19], v[18:19], 1.0, v[212:213] op_sel_hi:[1,0,1]
	v_pk_fma_f32 v[20:21], v[20:21], 1.0, v[214:215] op_sel_hi:[1,0,1]
	v_add_u32_e32 v146, 0xa0000, v220
	v_add_u32_e32 v147, 0x50000, v221
	v_add_u32_e32 v148, 0x2800, v223
	global_store_dwordx4 v146, v[30:33], s[48:49]
	global_store_dwordx4 v146, v[26:29], s[48:49] offset:64
	global_store_dwordx4 v146, v[22:25], s[48:49] offset:512
	global_store_dwordx4 v146, v[18:21], s[48:49] offset:576
	v_cvt_pk_bf16_f32 v224, v30, v31
	v_cvt_pk_bf16_f32 v225, v32, v33
	v_cvt_pk_bf16_f32 v226, v26, v27
	v_cvt_pk_bf16_f32 v227, v28, v29
	v_mul_f32_e32 v154, v31, v31
	v_mul_f32_e32 v155, v33, v33
	v_fmac_f32_e32 v154, v30, v30
	v_fmac_f32_e32 v155, v32, v32
	v_add_f32_e32 v156, v154, v155
	v_mul_f32_e32 v154, v27, v27
	v_mul_f32_e32 v155, v29, v29
	v_fmac_f32_e32 v154, v26, v26
	v_fmac_f32_e32 v155, v28, v28
	v_add_f32_e32 v154, v154, v155
	v_add_f32_e32 v156, v156, v154
	v_permlane16_swap_b32_e32 v224, v226
	v_permlane16_swap_b32_e32 v225, v227
	global_store_dwordx4 v147, v[224:227], s[50:51]
	v_cvt_pk_bf16_f32 v228, v22, v23
	v_cvt_pk_bf16_f32 v229, v24, v25
	v_cvt_pk_bf16_f32 v230, v18, v19
	v_cvt_pk_bf16_f32 v231, v20, v21
	v_mul_f32_e32 v154, v23, v23
	v_mul_f32_e32 v155, v25, v25
	v_fmac_f32_e32 v154, v22, v22
	v_fmac_f32_e32 v155, v24, v24
	v_add_f32_e32 v154, v154, v155
	v_add_f32_e32 v156, v156, v154
	v_mul_f32_e32 v154, v19, v19
	v_mul_f32_e32 v155, v21, v21
	v_fmac_f32_e32 v154, v18, v18
	v_fmac_f32_e32 v155, v20, v20
	v_add_f32_e32 v154, v154, v155
	v_add_f32_e32 v156, v156, v154
	v_permlane16_swap_b32_e32 v228, v230
	v_permlane16_swap_b32_e32 v229, v231
	global_store_dwordx4 v147, v[228:231], s[50:51] offset:256
	v_mov_b32_e32 v157, v156
	s_nop 1
	v_permlane16_swap_b32_e32 v157, v156
	v_add_f32_e32 v156, v157, v156
	v_mov_b32_e32 v157, v156
	s_nop 1
	v_permlane32_swap_b32_e32 v157, v156
	v_add_f32_e32 v156, v157, v156
	global_store_dword v148, v156, s[46:47]
	s_waitcnt vmcnt(28)
	v_pk_fma_f32 v[14:15], v[14:15], 1.0, v[134:135] op_sel_hi:[1,0,1]
	v_pk_fma_f32 v[16:17], v[16:17], 1.0, v[136:137] op_sel_hi:[1,0,1]
	v_pk_fma_f32 v[10:11], v[10:11], 1.0, v[138:139] op_sel_hi:[1,0,1]
	v_pk_fma_f32 v[12:13], v[12:13], 1.0, v[140:141] op_sel_hi:[1,0,1]
	v_pk_fma_f32 v[6:7], v[6:7], 1.0, v[186:187] op_sel_hi:[1,0,1]
	v_pk_fma_f32 v[8:9], v[8:9], 1.0, v[188:189] op_sel_hi:[1,0,1]
	v_pk_fma_f32 v[2:3], v[2:3], 1.0, v[190:191] op_sel_hi:[1,0,1]
	v_pk_fma_f32 v[4:5], v[4:5], 1.0, v[192:193] op_sel_hi:[1,0,1]
	v_add_u32_e32 v146, 0xb0000, v220
	v_add_u32_e32 v147, 0x58000, v221
	v_add_u32_e32 v148, 0x2c00, v223
	global_store_dwordx4 v146, v[14:17], s[48:49]
	global_store_dwordx4 v146, v[10:13], s[48:49] offset:64
	global_store_dwordx4 v146, v[6:9], s[48:49] offset:512
	global_store_dwordx4 v146, v[2:5], s[48:49] offset:576
	v_cvt_pk_bf16_f32 v224, v14, v15
	v_cvt_pk_bf16_f32 v225, v16, v17
	v_cvt_pk_bf16_f32 v226, v10, v11
	v_cvt_pk_bf16_f32 v227, v12, v13
	v_mul_f32_e32 v154, v15, v15
	v_mul_f32_e32 v155, v17, v17
	v_fmac_f32_e32 v154, v14, v14
	v_fmac_f32_e32 v155, v16, v16
	v_add_f32_e32 v156, v154, v155
	v_mul_f32_e32 v154, v11, v11
	v_mul_f32_e32 v155, v13, v13
	v_fmac_f32_e32 v154, v10, v10
	v_fmac_f32_e32 v155, v12, v12
	v_add_f32_e32 v154, v154, v155
	v_add_f32_e32 v156, v156, v154
	v_permlane16_swap_b32_e32 v224, v226
	v_permlane16_swap_b32_e32 v225, v227
	global_store_dwordx4 v147, v[224:227], s[50:51]
	v_cvt_pk_bf16_f32 v228, v6, v7
	v_cvt_pk_bf16_f32 v229, v8, v9
	v_cvt_pk_bf16_f32 v230, v2, v3
	v_cvt_pk_bf16_f32 v231, v4, v5
	v_mul_f32_e32 v154, v7, v7
	v_mul_f32_e32 v155, v9, v9
	v_fmac_f32_e32 v154, v6, v6
	v_fmac_f32_e32 v155, v8, v8
	v_add_f32_e32 v154, v154, v155
	v_add_f32_e32 v156, v156, v154
	v_mul_f32_e32 v154, v3, v3
	v_mul_f32_e32 v155, v5, v5
	v_fmac_f32_e32 v154, v2, v2
	v_fmac_f32_e32 v155, v4, v4
	v_add_f32_e32 v154, v154, v155
	v_add_f32_e32 v156, v156, v154
	v_permlane16_swap_b32_e32 v228, v230
	v_permlane16_swap_b32_e32 v229, v231
	global_store_dwordx4 v147, v[228:231], s[50:51] offset:256
	v_mov_b32_e32 v157, v156
	s_nop 1
	v_permlane16_swap_b32_e32 v157, v156
	v_add_f32_e32 v156, v157, v156
	v_mov_b32_e32 v157, v156
	s_nop 1
	v_permlane32_swap_b32_e32 v157, v156
	v_add_f32_e32 v156, v157, v156
	global_store_dword v148, v156, s[46:47]
	s_andn2_b64 vcc, exec, s[6:7]
	s_mov_b64 s[6:7], -1
	s_cbranch_vccnz .LBB0_609
	s_andn2_b64 vcc, exec, s[8:9]
	s_cbranch_vccnz .LBB0_608
	s_barrier
	s_branch .LBB0_608
